# grid barrier: non-leader pollers sleep 16 (instead of 1) between polls of the arrival counter
# speedup vs baseline: 1.0007x; 1.0007x over previous
; __device__ __forceinline__ unsigned xb_ld(unsigned* p)              { return __hip_atomic_load(p, __ATOMIC_RELAXED, __HIP_MEMORY_SCOPE_AGENT); }
; #define XB_SPIN(cond, bar) do { unsigned _sp = 0; while (cond) { __builtin_amdgcn_s_sleep(1); \
;     if ((++_sp & 255u) == 0u) { if (xb_ld(&(bar)[XB_TMO])) break; if (_sp > XB_SPIN_CAP) { atomicAdd(&(bar)[XB_TMO], 1u); break; } } } } while (0)
; __device__ __forceinline__ void xcd_barrier(const XcdBarrier& b) {
;     ...
;             XB_SPIN(xb_ld(&bar[XB_XGEN(b.x)]) == gen, bar);
.LBB0_81:
	s_and_b32 s14, s18, 0xff
	s_mov_b64 s[12:13], -1
	s_cmp_lg_u32 s14, 0
	s_mov_b64 s[44:45], -1
	s_sleep 16
	s_cbranch_scc0 .LBB0_84
	s_and_b64 vcc, exec, s[44:45]
	s_cbranch_vccz .LBB0_80

; __device__ __forceinline__ unsigned xb_ld(unsigned* p)              { return __hip_atomic_load(p, __ATOMIC_RELAXED, __HIP_MEMORY_SCOPE_AGENT); }
; #define XB_SPIN(cond, bar) do { unsigned _sp = 0; while (cond) { __builtin_amdgcn_s_sleep(1); \
;     if ((++_sp & 255u) == 0u) { if (xb_ld(&(bar)[XB_TMO])) break; if (_sp > XB_SPIN_CAP) { atomicAdd(&(bar)[XB_TMO], 1u); break; } } } } while (0)
; __device__ __forceinline__ void xcd_barrier(const XcdBarrier& b) {
;     ...
;             XB_SPIN(xb_ld(&bar[XB_XGEN(b.x)]) == gen, bar);
.LBB0_364:
	s_and_b32 s14, s18, 0xff
	s_mov_b64 s[12:13], -1
	s_cmp_lg_u32 s14, 0
	s_mov_b64 s[78:79], -1
	s_sleep 16
	s_cbranch_scc0 .LBB0_367
	s_and_b64 vcc, exec, s[78:79]
	s_cbranch_vccz .LBB0_363

; __device__ __forceinline__ unsigned xb_ld(unsigned* p)              { return __hip_atomic_load(p, __ATOMIC_RELAXED, __HIP_MEMORY_SCOPE_AGENT); }
; #define XB_SPIN(cond, bar) do { unsigned _sp = 0; while (cond) { __builtin_amdgcn_s_sleep(1); \
;     if ((++_sp & 255u) == 0u) { if (xb_ld(&(bar)[XB_TMO])) break; if (_sp > XB_SPIN_CAP) { atomicAdd(&(bar)[XB_TMO], 1u); break; } } } } while (0)
; __device__ __forceinline__ void xcd_barrier(const XcdBarrier& b) {
;     ...
;             XB_SPIN(xb_ld(&bar[XB_XGEN(b.x)]) == gen, bar);
.LBB0_487:
	s_and_b32 s14, s18, 0xff
	s_mov_b64 s[12:13], -1
	s_cmp_lg_u32 s14, 0
	s_mov_b64 s[58:59], -1
	s_sleep 16
	s_cbranch_scc0 .LBB0_490
	s_and_b64 vcc, exec, s[58:59]
	s_cbranch_vccz .LBB0_486

; __device__ __forceinline__ unsigned xb_ld(unsigned* p)              { return __hip_atomic_load(p, __ATOMIC_RELAXED, __HIP_MEMORY_SCOPE_AGENT); }
; #define XB_SPIN(cond, bar) do { unsigned _sp = 0; while (cond) { __builtin_amdgcn_s_sleep(1); \
;     if ((++_sp & 255u) == 0u) { if (xb_ld(&(bar)[XB_TMO])) break; if (_sp > XB_SPIN_CAP) { atomicAdd(&(bar)[XB_TMO], 1u); break; } } } } while (0)
; __device__ __forceinline__ void xcd_barrier(const XcdBarrier& b) {
;     ...
;             XB_SPIN(xb_ld(&bar[XB_XGEN(b.x)]) == gen, bar);
.LBB0_582:
	s_and_b32 s14, s18, 0xff
	s_mov_b64 s[12:13], -1
	s_cmp_lg_u32 s14, 0
	s_mov_b64 s[54:55], -1
	s_sleep 16
	s_cbranch_scc0 .LBB0_585
	s_and_b64 vcc, exec, s[54:55]
	s_cbranch_vccz .LBB0_581

; __device__ __forceinline__ unsigned xb_ld(unsigned* p)              { return __hip_atomic_load(p, __ATOMIC_RELAXED, __HIP_MEMORY_SCOPE_AGENT); }
; #define XB_SPIN(cond, bar) do { unsigned _sp = 0; while (cond) { __builtin_amdgcn_s_sleep(1); \
;     if ((++_sp & 255u) == 0u) { if (xb_ld(&(bar)[XB_TMO])) break; if (_sp > XB_SPIN_CAP) { atomicAdd(&(bar)[XB_TMO], 1u); break; } } } } while (0)
; __device__ __forceinline__ void xcd_barrier(const XcdBarrier& b) {
;     ...
;             XB_SPIN(xb_ld(&bar[XB_XGEN(b.x)]) == gen, bar);
.LBB0_783:
	s_and_b32 s14, s19, 0xff
	s_mov_b64 s[12:13], -1
	s_cmp_lg_u32 s14, 0
	s_mov_b64 s[54:55], -1
	s_sleep 16
	s_cbranch_scc0 .LBB0_786
	s_and_b64 vcc, exec, s[54:55]
	s_cbranch_vccz .LBB0_782

; __device__ __forceinline__ unsigned xb_ld(unsigned* p)              { return __hip_atomic_load(p, __ATOMIC_RELAXED, __HIP_MEMORY_SCOPE_AGENT); }
; #define XB_SPIN(cond, bar) do { unsigned _sp = 0; while (cond) { __builtin_amdgcn_s_sleep(1); \
;     if ((++_sp & 255u) == 0u) { if (xb_ld(&(bar)[XB_TMO])) break; if (_sp > XB_SPIN_CAP) { atomicAdd(&(bar)[XB_TMO], 1u); break; } } } } while (0)
; __device__ __forceinline__ void xcd_barrier(const XcdBarrier& b) {
;     ...
;             XB_SPIN(xb_ld(&bar[XB_XGEN(b.x)]) == gen, bar);
.LBB0_884:
	s_and_b32 s14, s21, 0xff
	s_mov_b64 s[12:13], -1
	s_cmp_lg_u32 s14, 0
	s_mov_b64 s[34:35], -1
	s_sleep 16
	s_cbranch_scc0 .LBB0_887
	s_and_b64 vcc, exec, s[34:35]
	s_cbranch_vccz .LBB0_883

; __device__ __forceinline__ unsigned xb_ld(unsigned* p)              { return __hip_atomic_load(p, __ATOMIC_RELAXED, __HIP_MEMORY_SCOPE_AGENT); }
; #define XB_SPIN(cond, bar) do { unsigned _sp = 0; while (cond) { __builtin_amdgcn_s_sleep(1); \
;     if ((++_sp & 255u) == 0u) { if (xb_ld(&(bar)[XB_TMO])) break; if (_sp > XB_SPIN_CAP) { atomicAdd(&(bar)[XB_TMO], 1u); break; } } } } while (0)
; __device__ __forceinline__ void xcd_barrier(const XcdBarrier& b) {
;     ...
;             XB_SPIN(xb_ld(&bar[XB_XGEN(b.x)]) == gen, bar);
.LBB0_971:
	s_and_b32 s14, s20, 0xff
	s_mov_b64 s[12:13], -1
	s_cmp_lg_u32 s14, 0
	s_mov_b64 s[48:49], -1
	s_sleep 16
	s_cbranch_scc0 .LBB0_974
	s_and_b64 vcc, exec, s[48:49]
	s_cbranch_vccz .LBB0_970

; __device__ __forceinline__ unsigned xb_ld(unsigned* p)              { return __hip_atomic_load(p, __ATOMIC_RELAXED, __HIP_MEMORY_SCOPE_AGENT); }
; #define XB_SPIN(cond, bar) do { unsigned _sp = 0; while (cond) { __builtin_amdgcn_s_sleep(1); \
;     if ((++_sp & 255u) == 0u) { if (xb_ld(&(bar)[XB_TMO])) break; if (_sp > XB_SPIN_CAP) { atomicAdd(&(bar)[XB_TMO], 1u); break; } } } } while (0)
; __device__ __forceinline__ void xcd_barrier(const XcdBarrier& b) {
;     ...
;             XB_SPIN(xb_ld(&bar[XB_XGEN(b.x)]) == gen, bar);
.LBB0_1039:
	s_and_b32 s22, s3, 0xff
	s_mov_b64 s[12:13], -1
	s_cmp_lg_u32 s22, 0
	s_mov_b64 s[24:25], -1
	s_sleep 16
	s_cbranch_scc0 .LBB0_1042
	s_and_b64 vcc, exec, s[24:25]
	s_cbranch_vccz .LBB0_1038
